# v65 + k0 norm context-row fold (11 split-K slices): 22 loads per column half issued together instead of a 2-3-deep dependent chain
# speedup vs baseline: 1.0052x; 1.0028x over previous
.LBB0_558:
	s_cmpk_lt_i32 s14, 0x4000
	s_cselect_b64 s[16:17], -1, 0
	s_or_b64 s[16:17], s[8:9], s[16:17]
	s_and_b64 vcc, exec, s[16:17]
	s_cbranch_vccnz .LBB0_545
	s_add_i32 s20, s14, 0xffffc000
	s_lshl_b64 s[16:17], s[20:21], 12
	v_lshl_add_u64 v[82:83], v[98:99], 0, s[16:17]
	s_mov_b32 s15, s21
	s_lshl_b64 s[14:15], s[14:15], 11
	s_mov_b64 s[16:17], 0x400000
	v_mov_b64_e32 v[84:85], v[82:83]
	global_load_dwordx4 v[118:121], v[84:85], off
	global_load_dwordx4 v[122:125], v[84:85], off offset:16
	v_lshl_add_u64 v[84:85], v[84:85], 0, s[16:17]
	global_load_dwordx4 v[126:129], v[84:85], off
	global_load_dwordx4 v[130:133], v[84:85], off offset:16
	v_lshl_add_u64 v[84:85], v[84:85], 0, s[16:17]
	global_load_dwordx4 v[134:137], v[84:85], off
	global_load_dwordx4 v[138:141], v[84:85], off offset:16
	v_lshl_add_u64 v[84:85], v[84:85], 0, s[16:17]
	global_load_dwordx4 v[142:145], v[84:85], off
	global_load_dwordx4 v[146:149], v[84:85], off offset:16
	v_lshl_add_u64 v[84:85], v[84:85], 0, s[16:17]
	global_load_dwordx4 v[150:153], v[84:85], off
	global_load_dwordx4 v[154:157], v[84:85], off offset:16
	v_lshl_add_u64 v[84:85], v[84:85], 0, s[16:17]
	global_load_dwordx4 v[158:161], v[84:85], off
	global_load_dwordx4 v[162:165], v[84:85], off offset:16
	v_lshl_add_u64 v[84:85], v[84:85], 0, s[16:17]
	global_load_dwordx4 v[166:169], v[84:85], off
	global_load_dwordx4 v[170:173], v[84:85], off offset:16
	v_lshl_add_u64 v[84:85], v[84:85], 0, s[16:17]
	global_load_dwordx4 v[174:177], v[84:85], off
	global_load_dwordx4 v[178:181], v[84:85], off offset:16
	v_lshl_add_u64 v[84:85], v[84:85], 0, s[16:17]
	global_load_dwordx4 v[182:185], v[84:85], off
	global_load_dwordx4 v[186:189], v[84:85], off offset:16
	v_lshl_add_u64 v[84:85], v[84:85], 0, s[16:17]
	global_load_dwordx4 v[190:193], v[84:85], off
	global_load_dwordx4 v[194:197], v[84:85], off offset:16
	v_lshl_add_u64 v[84:85], v[84:85], 0, s[16:17]
	global_load_dwordx4 v[198:201], v[84:85], off
	global_load_dwordx4 v[202:205], v[84:85], off offset:16
	global_load_dwordx4 v[86:89], v[94:95], off offset:-4096
	s_waitcnt vmcnt(22)
	v_pk_add_f32 v[66:67], v[118:119], 0 op_sel_hi:[1,0]
	v_pk_add_f32 v[68:69], v[120:121], 0 op_sel_hi:[1,0]
	s_waitcnt vmcnt(21)
	v_pk_add_f32 v[70:71], v[122:123], 0 op_sel_hi:[1,0]
	v_pk_add_f32 v[72:73], v[124:125], 0 op_sel_hi:[1,0]
	global_load_dwordx4 v[118:121], v[94:95], off offset:-4080
	s_waitcnt vmcnt(21)
	v_pk_add_f32 v[66:67], v[66:67], v[126:127]
	v_pk_add_f32 v[68:69], v[68:69], v[128:129]
	s_waitcnt vmcnt(20)
	v_pk_add_f32 v[70:71], v[70:71], v[130:131]
	v_pk_add_f32 v[72:73], v[72:73], v[132:133]
	s_waitcnt vmcnt(19)
	v_pk_add_f32 v[66:67], v[66:67], v[134:135]
	v_pk_add_f32 v[68:69], v[68:69], v[136:137]
	s_waitcnt vmcnt(18)
	v_pk_add_f32 v[70:71], v[70:71], v[138:139]
	v_pk_add_f32 v[72:73], v[72:73], v[140:141]
	s_waitcnt vmcnt(17)
	v_pk_add_f32 v[66:67], v[66:67], v[142:143]
	v_pk_add_f32 v[68:69], v[68:69], v[144:145]
	s_waitcnt vmcnt(16)
	v_pk_add_f32 v[70:71], v[70:71], v[146:147]
	v_pk_add_f32 v[72:73], v[72:73], v[148:149]
	s_waitcnt vmcnt(15)
	v_pk_add_f32 v[66:67], v[66:67], v[150:151]
	v_pk_add_f32 v[68:69], v[68:69], v[152:153]
	s_waitcnt vmcnt(14)
	v_pk_add_f32 v[70:71], v[70:71], v[154:155]
	v_pk_add_f32 v[72:73], v[72:73], v[156:157]
	s_waitcnt vmcnt(13)
	v_pk_add_f32 v[66:67], v[66:67], v[158:159]
	v_pk_add_f32 v[68:69], v[68:69], v[160:161]
	s_waitcnt vmcnt(12)
	v_pk_add_f32 v[70:71], v[70:71], v[162:163]
	v_pk_add_f32 v[72:73], v[72:73], v[164:165]
	s_waitcnt vmcnt(11)
	v_pk_add_f32 v[66:67], v[66:67], v[166:167]
	v_pk_add_f32 v[68:69], v[68:69], v[168:169]
	s_waitcnt vmcnt(10)
	v_pk_add_f32 v[70:71], v[70:71], v[170:171]
	v_pk_add_f32 v[72:73], v[72:73], v[172:173]
	s_waitcnt vmcnt(9)
	v_pk_add_f32 v[66:67], v[66:67], v[174:175]
	v_pk_add_f32 v[68:69], v[68:69], v[176:177]
	s_waitcnt vmcnt(8)
	v_pk_add_f32 v[70:71], v[70:71], v[178:179]
	v_pk_add_f32 v[72:73], v[72:73], v[180:181]
	s_waitcnt vmcnt(7)
	v_pk_add_f32 v[66:67], v[66:67], v[182:183]
	v_pk_add_f32 v[68:69], v[68:69], v[184:185]
	s_waitcnt vmcnt(6)
	v_pk_add_f32 v[70:71], v[70:71], v[186:187]
	v_pk_add_f32 v[72:73], v[72:73], v[188:189]
	s_waitcnt vmcnt(5)
	v_pk_add_f32 v[66:67], v[66:67], v[190:191]
	v_pk_add_f32 v[68:69], v[68:69], v[192:193]
	s_waitcnt vmcnt(4)
	v_pk_add_f32 v[70:71], v[70:71], v[194:195]
	v_pk_add_f32 v[72:73], v[72:73], v[196:197]
	s_waitcnt vmcnt(3)
	v_pk_add_f32 v[66:67], v[66:67], v[198:199]
	v_pk_add_f32 v[68:69], v[68:69], v[200:201]
	s_waitcnt vmcnt(2)
	v_pk_add_f32 v[70:71], v[70:71], v[202:203]
	v_pk_add_f32 v[72:73], v[72:73], v[204:205]
	s_waitcnt vmcnt(1)
	v_pk_fma_f32 v[112:113], v[66:67], v[86:87], v[112:113]
	v_pk_fma_f32 v[116:117], v[68:69], v[88:89], v[116:117]
	s_waitcnt vmcnt(0)
	v_pk_fma_f32 v[110:111], v[70:71], v[118:119], v[110:111]
	v_pk_fma_f32 v[114:115], v[72:73], v[120:121], v[114:115]
	v_mov_b64_e32 v[84:85], v[82:83]
	global_load_dwordx4 v[118:121], v[84:85], off offset:2048
	global_load_dwordx4 v[122:125], v[84:85], off offset:2064
	v_lshl_add_u64 v[84:85], v[84:85], 0, s[16:17]
	global_load_dwordx4 v[126:129], v[84:85], off offset:2048
	global_load_dwordx4 v[130:133], v[84:85], off offset:2064
	v_lshl_add_u64 v[84:85], v[84:85], 0, s[16:17]
	global_load_dwordx4 v[134:137], v[84:85], off offset:2048
	global_load_dwordx4 v[138:141], v[84:85], off offset:2064
	v_lshl_add_u64 v[84:85], v[84:85], 0, s[16:17]
	global_load_dwordx4 v[142:145], v[84:85], off offset:2048
	global_load_dwordx4 v[146:149], v[84:85], off offset:2064
	v_lshl_add_u64 v[84:85], v[84:85], 0, s[16:17]
	global_load_dwordx4 v[150:153], v[84:85], off offset:2048
	global_load_dwordx4 v[154:157], v[84:85], off offset:2064
	v_lshl_add_u64 v[84:85], v[84:85], 0, s[16:17]
	global_load_dwordx4 v[158:161], v[84:85], off offset:2048
	global_load_dwordx4 v[162:165], v[84:85], off offset:2064
	v_lshl_add_u64 v[84:85], v[84:85], 0, s[16:17]
	global_load_dwordx4 v[166:169], v[84:85], off offset:2048
	global_load_dwordx4 v[170:173], v[84:85], off offset:2064
	v_lshl_add_u64 v[84:85], v[84:85], 0, s[16:17]
	global_load_dwordx4 v[174:177], v[84:85], off offset:2048
	global_load_dwordx4 v[178:181], v[84:85], off offset:2064
	v_lshl_add_u64 v[84:85], v[84:85], 0, s[16:17]
	global_load_dwordx4 v[182:185], v[84:85], off offset:2048
	global_load_dwordx4 v[186:189], v[84:85], off offset:2064
	v_lshl_add_u64 v[84:85], v[84:85], 0, s[16:17]
	global_load_dwordx4 v[190:193], v[84:85], off offset:2048
	global_load_dwordx4 v[194:197], v[84:85], off offset:2064
	v_lshl_add_u64 v[84:85], v[84:85], 0, s[16:17]
	global_load_dwordx4 v[198:201], v[84:85], off offset:2048
	global_load_dwordx4 v[202:205], v[84:85], off offset:2064
	global_load_dwordx4 v[86:89], v[94:95], off offset:-2048
	s_waitcnt vmcnt(22)
	v_pk_add_f32 v[74:75], v[118:119], 0 op_sel_hi:[1,0]
	v_pk_add_f32 v[76:77], v[120:121], 0 op_sel_hi:[1,0]
	s_waitcnt vmcnt(21)
	v_pk_add_f32 v[78:79], v[122:123], 0 op_sel_hi:[1,0]
	v_pk_add_f32 v[80:81], v[124:125], 0 op_sel_hi:[1,0]
	global_load_dwordx4 v[118:121], v[94:95], off offset:-2032
	s_waitcnt vmcnt(21)
	v_pk_add_f32 v[74:75], v[74:75], v[126:127]
	v_pk_add_f32 v[76:77], v[76:77], v[128:129]
	s_waitcnt vmcnt(20)
	v_pk_add_f32 v[78:79], v[78:79], v[130:131]
	v_pk_add_f32 v[80:81], v[80:81], v[132:133]
	s_waitcnt vmcnt(19)
	v_pk_add_f32 v[74:75], v[74:75], v[134:135]
	v_pk_add_f32 v[76:77], v[76:77], v[136:137]
	s_waitcnt vmcnt(18)
	v_pk_add_f32 v[78:79], v[78:79], v[138:139]
	v_pk_add_f32 v[80:81], v[80:81], v[140:141]
	s_waitcnt vmcnt(17)
	v_pk_add_f32 v[74:75], v[74:75], v[142:143]
	v_pk_add_f32 v[76:77], v[76:77], v[144:145]
	s_waitcnt vmcnt(16)
	v_pk_add_f32 v[78:79], v[78:79], v[146:147]
	v_pk_add_f32 v[80:81], v[80:81], v[148:149]
	s_waitcnt vmcnt(15)
	v_pk_add_f32 v[74:75], v[74:75], v[150:151]
	v_pk_add_f32 v[76:77], v[76:77], v[152:153]
	s_waitcnt vmcnt(14)
	v_pk_add_f32 v[78:79], v[78:79], v[154:155]
	v_pk_add_f32 v[80:81], v[80:81], v[156:157]
	s_waitcnt vmcnt(13)
	v_pk_add_f32 v[74:75], v[74:75], v[158:159]
	v_pk_add_f32 v[76:77], v[76:77], v[160:161]
	s_waitcnt vmcnt(12)
	v_pk_add_f32 v[78:79], v[78:79], v[162:163]
	v_pk_add_f32 v[80:81], v[80:81], v[164:165]
	s_waitcnt vmcnt(11)
	v_pk_add_f32 v[74:75], v[74:75], v[166:167]
	v_pk_add_f32 v[76:77], v[76:77], v[168:169]
	s_waitcnt vmcnt(10)
	v_pk_add_f32 v[78:79], v[78:79], v[170:171]
	v_pk_add_f32 v[80:81], v[80:81], v[172:173]
	s_waitcnt vmcnt(9)
	v_pk_add_f32 v[74:75], v[74:75], v[174:175]
	v_pk_add_f32 v[76:77], v[76:77], v[176:177]
	s_waitcnt vmcnt(8)
	v_pk_add_f32 v[78:79], v[78:79], v[178:179]
	v_pk_add_f32 v[80:81], v[80:81], v[180:181]
	s_waitcnt vmcnt(7)
	v_pk_add_f32 v[74:75], v[74:75], v[182:183]
	v_pk_add_f32 v[76:77], v[76:77], v[184:185]
	s_waitcnt vmcnt(6)
	v_pk_add_f32 v[78:79], v[78:79], v[186:187]
	v_pk_add_f32 v[80:81], v[80:81], v[188:189]
	s_waitcnt vmcnt(5)
	v_pk_add_f32 v[74:75], v[74:75], v[190:191]
	v_pk_add_f32 v[76:77], v[76:77], v[192:193]
	s_waitcnt vmcnt(4)
	v_pk_add_f32 v[78:79], v[78:79], v[194:195]
	v_pk_add_f32 v[80:81], v[80:81], v[196:197]
	s_waitcnt vmcnt(3)
	v_pk_add_f32 v[74:75], v[74:75], v[198:199]
	v_pk_add_f32 v[76:77], v[76:77], v[200:201]
	s_waitcnt vmcnt(2)
	v_pk_add_f32 v[78:79], v[78:79], v[202:203]
	v_pk_add_f32 v[80:81], v[80:81], v[204:205]
	s_waitcnt vmcnt(1)
	v_pk_fma_f32 v[106:107], v[74:75], v[86:87], v[106:107]
	v_pk_fma_f32 v[108:109], v[76:77], v[88:89], v[108:109]
	s_waitcnt vmcnt(0)
	v_pk_fma_f32 v[102:103], v[78:79], v[118:119], v[102:103]
	v_pk_fma_f32 v[104:105], v[80:81], v[120:121], v[104:105]
	v_lshl_add_u64 v[70:71], v[92:93], 0, s[14:15]
	v_cvt_pk_bf16_f32 v66, v112, v113
	v_cvt_pk_bf16_f32 v67, v116, v117
	v_cvt_pk_bf16_f32 v68, v110, v111
	v_cvt_pk_bf16_f32 v69, v114, v115
	global_store_dwordx4 v[70:71], v[66:69], off
	s_nop 1
	v_cvt_pk_bf16_f32 v66, v106, v107
	v_cvt_pk_bf16_f32 v67, v108, v109
	v_cvt_pk_bf16_f32 v68, v102, v103
	v_cvt_pk_bf16_f32 v69, v104, v105
	global_store_dwordx4 v[70:71], v[66:69], off offset:1024
	s_branch .LBB0_545
